# SEAM4 same-XCD 4-workgroup counter; path decision now global (all eight residues must each report one XCD), else everyone takes the grid barrier
# speedup vs baseline: 1.0084x; 1.0004x over previous
.LBB0_511:
	s_cmp_gt_i32 s91, 5
	s_cselect_b64 s[4:5], -1, 0
	s_and_b64 s[0:1], s[0:1], s[4:5]
	s_andn2_b64 vcc, exec, s[0:1]
	s_cbranch_vccnz .LBB0_565
	s_waitcnt vmcnt(0)
	s_waitcnt vmcnt(0) lgkmcnt(0)
	s_barrier
	s_and_saveexec_b64 s[0:1], s[84:85]
	s_cbranch_execz .LBB0_564
	v_mov_b32_e32 v0, 0xe000
	global_load_dwordx4 v[4:7], v0, s[88:89] sc1
	global_load_dwordx4 v[8:11], v0, s[88:89] offset:16 sc1
	global_load_dwordx4 v[12:15], v0, s[88:89] offset:32 sc1
	global_load_dwordx4 v[16:19], v0, s[88:89] offset:48 sc1
	s_and_b32 s98, s2, 7
	s_lshl_b32 s98, s98, 3
	s_bfe_u32 s99, s2, 0x30003
	s_add_i32 s98, s98, s99
	s_lshl_b32 s98, s98, 6
	s_add_i32 s98, s98, 0xd000
	v_mov_b32_e32 v2, s98
	v_mov_b32_e32 v3, 1
	s_waitcnt vmcnt(0)
	v_add_u32_e32 v4, v4, v5
	v_add_u32_e32 v6, v6, v7
	v_add_u32_e32 v8, v8, v9
	v_add_u32_e32 v10, v10, v11
	v_add_u32_e32 v12, v12, v13
	v_add_u32_e32 v14, v14, v15
	v_add_u32_e32 v16, v16, v17
	v_add_u32_e32 v18, v18, v19
	v_xor_b32_e32 v4, 17, v4
	v_xor_b32_e32 v6, 17, v6
	v_xor_b32_e32 v8, 17, v8
	v_xor_b32_e32 v10, 17, v10
	v_xor_b32_e32 v12, 17, v12
	v_xor_b32_e32 v14, 17, v14
	v_xor_b32_e32 v16, 17, v16
	v_xor_b32_e32 v18, 17, v18
	v_or3_b32 v4, v4, v6, v8
	v_or3_b32 v10, v10, v12, v14
	v_or3_b32 v4, v4, v16, v18
	v_or_b32_e32 v1, v4, v10
	v_cmp_ne_u32_e32 vcc, 0, v1
	s_cbranch_vccnz .Lg4_orig
	global_atomic_add v2, v3, s[88:89]
